# scan stage 5: second-half operand LDS reads issued at the stage top
# baseline (speedup 1.0000x reference)
.LBB0_231:
	s_or_b64 exec, exec, s[48:49]
	v_add_u32_e32 v4, 0x9800, v215
	ds_read_b128 v[238:241], v163 offset:64
	ds_read_b128 v[242:245], v162 offset:64
	ds_read2_b64 v[246:249], v4 offset0:88 offset1:92
	ds_read_b128 v[34:37], v161 offset:51072
	ds_read_b128 v[38:41], v161 offset:51136
	ds_read_b128 v[58:61], v161 offset:51200
	v_add_u32_e32 v3, 0x7800, v215
	s_waitcnt lgkmcnt(2)
	v_pk_mul_f32 v[48:49], v[48:49], v[36:37]
	s_waitcnt lgkmcnt(1)
	v_pk_mul_f32 v[44:45], v[64:65], v[40:41]
	v_pk_mul_f32 v[42:43], v[56:57], v[38:39]
	ds_read2_b64 v[38:41], v3 offset0:240 offset1:244
	v_pk_mul_f32 v[46:47], v[46:47], v[34:35]
	s_waitcnt lgkmcnt(1)
	v_pk_mul_f32 v[36:37], v[62:63], v[60:61]
	v_pk_mul_f32 v[34:35], v[54:55], v[58:59]
	ds_read2_b64 v[58:61], v4 offset0:80 offset1:84
	ds_read_b128 v[54:57], v161 offset:51264
	ds_read2_b64 v[70:73], v3 offset0:248 offset1:252
	v_cvt_pk_f16_f32 v65, v44, v45
	v_cvt_pk_f16_f32 v63, v48, v49
	v_cvt_pk_f16_f32 v64, v42, v43
	v_cvt_pk_f16_f32 v62, v46, v47
	ds_read_b128 v[74:77], v163
	s_cmp_lt_i32 s45, 2
	s_waitcnt lgkmcnt(4)
	v_mfma_f32_16x16x32_f16 v[66:69], v[38:41], v[62:65], 0
	s_waitcnt lgkmcnt(2)
	v_pk_mul_f32 v[40:41], v[52:53], v[56:57]
	v_pk_mul_f32 v[38:39], v[50:51], v[54:55]
	ds_read_b128 v[50:53], v162
	v_mfma_f32_16x16x32_f16 v[54:57], v[58:61], v[62:65], 0
	v_cvt_pk_f16_f32 v65, v40, v41
	v_cvt_pk_f16_f32 v63, v36, v37
	v_cvt_pk_f16_f32 v64, v38, v39
	v_cvt_pk_f16_f32 v62, v34, v35
	s_waitcnt lgkmcnt(2)
	s_nop 0
	v_mfma_f32_16x16x32_f16 v[58:61], v[70:73], v[62:65], v[66:69]
	s_waitcnt lgkmcnt(0)
	v_mfma_f32_16x16x32_f16 v[50:53], v[50:53], v[74:77], 0
	v_mfma_f32_16x16x32_f16 v[50:53], v[242:245], v[238:241], v[50:53]
	v_mfma_f32_16x16x32_f16 v[54:57], v[246:249], v[62:65], v[54:57]
	s_nop 2
	s_cbranch_scc1 .LBB0_235
	s_cmp_eq_u32 s45, 2
	s_cselect_b64 s[88:89], -1, 0
	s_cbranch_execz .LBB0_236
	s_branch .LBB0_237
